# HG3 inter-chunk part (both directions): state fragments of k-steps 1..3 prefetched 12-20 deep instead of 2-5; in-place accumulation
# speedup vs baseline: 1.0117x; 1.0038x over previous
; DI f32x4 mfma32(bf16x8 a, bf16x8 b, f32x4 c) { return __builtin_amdgcn_mfma_f32_16x16x32_bf16(a, b, c, 0, 0, 0); }
; DI void phase_hg3(const Ctx& c, LAS unsigned char* lds, int g, int l, const bf16* PROJ, const bf16* ST, const bf16* RT, const float* GC, const bf16* KT1, const bf16* QTB, bf16* MIX, int bid, int nb, int tid) {
;     ...
; #pragma unroll
;             for (int ks = 0; ks < 4; ++ks) {
;                 if (ks < 3) {
; #pragma unroll
;                     for (int vt = 0; vt < 8; ++vt) sa[(ks + 1) & 1][vt] = *(const bf16x8*)(ST + su * 16384 + ((vt * 4 + ks + 1) * 64 + lane) * 8); }
; #pragma unroll
;                 for (int vt = 0; vt < 8; ++vt) o[vt] = mfma32(sa[ks & 1][vt], qt[ks], o[vt]);
;             }
;             { const int sq_ = cgk / ncs, cs = cgk - sq_ * ncs, p = dir ? ncs - 1 - cs : cs, blk = p >> 3;
;               if (blk > 0) { const size_t rr = (size_t)((sq_ * 8 + h * 2 + dir) * rps + blk);
.LBB0_400:
	s_or_b64 exec, exec, vcc
	s_mov_b64 vcc, 0x1000
	v_lshl_add_u64 v[138:139], vcc, 0, v[136:137]
	s_mov_b64 vcc, 0x3000
	v_lshl_add_u64 v[140:141], vcc, 0, v[136:137]
	s_mov_b64 vcc, 0x5000
	v_lshl_add_u64 v[202:203], vcc, 0, v[136:137]
	s_mov_b64 vcc, 0x7000
	v_lshl_add_u64 v[204:205], vcc, 0, v[136:137]
	global_load_dwordx4 v[86:89], v[138:139], off offset:-3072
	global_load_dwordx4 v[98:101], v[138:139], off offset:1024
	global_load_dwordx4 v[102:105], v[140:141], off offset:-3072
	global_load_dwordx4 v[106:109], v[140:141], off offset:1024
	global_load_dwordx4 v[110:113], v[202:203], off offset:-3072
	global_load_dwordx4 v[114:117], v[202:203], off offset:1024
	global_load_dwordx4 v[90:93], v[204:205], off offset:-3072
	global_load_dwordx4 v[94:97], v[204:205], off offset:1024
	global_load_dwordx4 v[118:121], v[138:139], off offset:-2048
	global_load_dwordx4 v[122:125], v[138:139], off offset:2048
	global_load_dwordx4 v[126:129], v[140:141], off offset:-2048
	global_load_dwordx4 v[130:133], v[140:141], off offset:2048
	s_waitcnt vmcnt(12)
	v_mfma_f32_16x16x32_bf16 v[82:85], v[50:53], v[18:21], v[82:85]
	s_movk_i32 s96, 0x3000
	s_movk_i32 s34, 0x4000
	v_mfma_f32_16x16x32_bf16 v[74:77], v[46:49], v[18:21], v[74:77]
	s_movk_i32 s60, 0x5000
	s_movk_i32 s59, 0x6000
	v_mfma_f32_16x16x32_bf16 v[66:69], v[42:45], v[18:21], v[66:69]
	s_movk_i32 s61, 0x7000
	s_abs_i32 s18, s0
	v_mfma_f32_16x16x32_bf16 v[70:73], v[34:37], v[18:21], v[70:73]
	v_readlane_b32 s19, v254, 52
	s_mul_hi_u32 s19, s18, s19
	v_mfma_f32_16x16x32_bf16 v[78:81], v[38:41], v[18:21], v[78:81]
	v_readlane_b32 s33, v254, 53
	s_mul_i32 s26, s19, s33
	v_mfma_f32_16x16x32_bf16 v[62:65], v[26:29], v[18:21], v[62:65]
	s_sub_i32 s18, s18, s26
	s_ashr_i32 s1, s0, 31
	v_mfma_f32_16x16x32_bf16 v[58:61], v[30:33], v[18:21], v[58:61]
	s_add_i32 s26, s19, 1
	s_sub_i32 s27, s18, s33
	v_mfma_f32_16x16x32_bf16 v[54:57], v[22:25], v[18:21], v[54:57]
	s_cmp_ge_u32 s18, s33
	s_cselect_b32 s19, s26, s19
	global_load_dwordx4 v[50:53], v[202:203], off offset:-2048
	global_load_dwordx4 v[46:49], v[202:203], off offset:2048
	global_load_dwordx4 v[42:45], v[204:205], off offset:-2048
	global_load_dwordx4 v[34:37], v[204:205], off offset:2048
	global_load_dwordx4 v[38:41], v[138:139], off offset:-1024
	global_load_dwordx4 v[26:29], v[138:139], off offset:3072
	global_load_dwordx4 v[30:33], v[140:141], off offset:-1024
	global_load_dwordx4 v[22:25], v[140:141], off offset:3072
	s_waitcnt vmcnt(19)
	v_mfma_f32_16x16x32_bf16 v[82:85], v[86:89], v[14:17], v[82:85]
	s_cselect_b32 s18, s27, s18
	s_add_i32 s26, s19, 1
	s_waitcnt vmcnt(18)
	v_mfma_f32_16x16x32_bf16 v[74:77], v[98:101], v[14:17], v[74:77]
	s_cmp_ge_u32 s18, s33
	s_cselect_b32 s18, s26, s19
	s_waitcnt vmcnt(17)
	v_mfma_f32_16x16x32_bf16 v[66:69], v[102:105], v[14:17], v[66:69]
	s_xor_b32 s18, s18, s1
	s_sub_i32 s1, s18, s1
	s_waitcnt vmcnt(16)
	v_mfma_f32_16x16x32_bf16 v[70:73], v[106:109], v[14:17], v[70:73]
	v_readlane_b32 s18, v254, 38
	s_lshl_b32 s18, s1, s18
	s_waitcnt vmcnt(15)
	v_mfma_f32_16x16x32_bf16 v[78:81], v[110:113], v[14:17], v[78:81]
	s_sub_i32 s33, s0, s18
	s_ashr_i32 s0, s33, 3
	s_waitcnt vmcnt(14)
	v_mfma_f32_16x16x32_bf16 v[62:65], v[114:117], v[14:17], v[62:65]
	s_movk_i32 s35, 0x2000
	s_cmp_lt_i32 s0, 1
	s_waitcnt vmcnt(13)
	v_mfma_f32_16x16x32_bf16 v[58:61], v[90:93], v[14:17], v[58:61]
	s_waitcnt vmcnt(12)
	v_mfma_f32_16x16x32_bf16 v[54:57], v[94:97], v[14:17], v[54:57]
	global_load_dwordx4 v[86:89], v[202:203], off offset:-1024
	global_load_dwordx4 v[98:101], v[202:203], off offset:3072
	global_load_dwordx4 v[102:105], v[204:205], off offset:-1024
	global_load_dwordx4 v[106:109], v[204:205], off offset:3072
	s_waitcnt vmcnt(15)
	v_mfma_f32_16x16x32_bf16 v[82:85], v[118:121], v[10:13], v[82:85]
	s_waitcnt vmcnt(14)
	v_mfma_f32_16x16x32_bf16 v[74:77], v[122:125], v[10:13], v[74:77]
	s_waitcnt vmcnt(13)
	v_mfma_f32_16x16x32_bf16 v[66:69], v[126:129], v[10:13], v[66:69]
	s_waitcnt vmcnt(12)
	v_mfma_f32_16x16x32_bf16 v[70:73], v[130:133], v[10:13], v[70:73]
	s_waitcnt vmcnt(11)
	v_mfma_f32_16x16x32_bf16 v[78:81], v[50:53], v[10:13], v[78:81]
	s_waitcnt vmcnt(10)
	v_mfma_f32_16x16x32_bf16 v[62:65], v[46:49], v[10:13], v[62:65]
	s_waitcnt vmcnt(9)
	v_mfma_f32_16x16x32_bf16 v[58:61], v[42:45], v[10:13], v[58:61]
	s_waitcnt vmcnt(8)
	v_mfma_f32_16x16x32_bf16 v[54:57], v[34:37], v[10:13], v[54:57]
	s_waitcnt vmcnt(0)
	v_mfma_f32_16x16x32_bf16 v[94:97], v[102:105], v[6:9], v[58:61]
	v_mfma_f32_16x16x32_bf16 v[58:61], v[98:101], v[6:9], v[62:65]
	v_mfma_f32_16x16x32_bf16 v[62:65], v[22:25], v[6:9], v[70:73]
	v_mfma_f32_16x16x32_bf16 v[70:73], v[26:29], v[6:9], v[74:77]
	v_mfma_f32_16x16x32_bf16 v[74:77], v[30:33], v[6:9], v[66:69]
	v_mfma_f32_16x16x32_bf16 v[66:69], v[38:41], v[6:9], v[82:85]
	v_mfma_f32_16x16x32_bf16 v[90:93], v[106:109], v[6:9], v[54:57]
	v_mfma_f32_16x16x32_bf16 v[54:57], v[86:89], v[6:9], v[78:81]
	v_lshlrev_b32_e32 v206, 1, v149
	v_lshl_add_u32 v181, s1, 3, v206
	s_cbranch_scc1 .LBB0_404
; DI f32x4 mfma32(bf16x8 a, bf16x8 b, f32x4 c) { return __builtin_amdgcn_mfma_f32_16x16x32_bf16(a, b, c, 0, 0, 0); }
; DI void phase_hg3(const Ctx& c, LAS unsigned char* lds, int g, int l, const bf16* PROJ, const bf16* ST, const bf16* RT, const float* GC, const bf16* KT1, const bf16* QTB, bf16* MIX, int bid, int nb, int tid) {
;     ...
;             { const int sq_ = cgk / ncs, cs = cgk - sq_ * ncs, p = dir ? ncs - 1 - cs : cs, blk = p >> 3;
;               if (blk > 0) { const size_t rr = (size_t)((sq_ * 8 + h * 2 + dir) * rps + blk);
; #pragma unroll
;                 for (int ks = 0; ks < 4; ++ks) { const float* gp = GC + su * 128 + ks * 32 + gq * 8; const bf16x8 q2 = scale8(qt[ks], *(const f32x4*)gp, *(const f32x4*)(gp + 4));
; #pragma unroll
;                     for (int vt = 0; vt < 8; ++vt) sa[0][vt] = *(const bf16x8*)(RT + rr * 16384 + ((vt * 4 + ks) * 64 + lane) * 8);
; #pragma unroll
;                     for (int vt = 0; vt < 8; ++vt) o[vt] = mfma32(sa[0][vt], q2, o[vt]); } } }
	v_readlane_b32 s1, v254, 44
	s_nop 0
	v_lshlrev_b64 v[24:25], 10, v[134:135]
	v_lshl_add_u64 v[50:51], v[2:3], 0, v[24:25]
	v_lshlrev_b32_e32 v22, s1, v181
	v_add_u32_e32 v22, s0, v22
	v_ashrrev_i32_e32 v23, 31, v22
	v_lshlrev_b64 v[30:31], 15, v[22:23]
	v_lshl_add_u64 v[52:53], v[146:147], 0, v[30:31]
	s_movk_i32 s18, 0x2000
	s_mov_b64 vcc, 0x1000
	v_lshl_add_u64 v[80:81], vcc, 0, v[52:53]
	s_mov_b64 vcc, 0x3000
	v_lshl_add_u64 v[84:85], vcc, 0, v[52:53]
	s_mov_b64 vcc, 0x5000
	v_lshl_add_u64 v[88:89], vcc, 0, v[52:53]
	s_mov_b64 vcc, 0x7000
	v_lshl_add_u64 v[78:79], vcc, 0, v[52:53]
	global_load_dwordx4 v[22:25], v[50:51], off offset:16
	global_load_dwordx4 v[26:29], v[50:51], off
	global_load_dwordx4 v[30:33], v[50:51], off offset:144
	global_load_dwordx4 v[34:37], v[50:51], off offset:128
	global_load_dwordx4 v[38:41], v[50:51], off offset:272
	global_load_dwordx4 v[42:45], v[50:51], off offset:256
	global_load_dwordx4 v[46:49], v[50:51], off offset:400
	global_load_dwordx4 v[100:103], v[50:51], off offset:384
	global_load_dwordx4 v[104:107], v[80:81], off offset:-4096
	global_load_dwordx4 v[108:111], v[80:81], off
	global_load_dwordx4 v[112:115], v[84:85], off offset:-4096
	global_load_dwordx4 v[116:119], v[84:85], off
	global_load_dwordx4 v[120:123], v[88:89], off offset:-4096
	global_load_dwordx4 v[124:127], v[88:89], off
	global_load_dwordx4 v[128:131], v[78:79], off offset:-4096
	global_load_dwordx4 v[138:141], v[78:79], off
	s_waitcnt vmcnt(8)
	v_lshlrev_b32_e32 v132, 16, v18
	v_and_b32_e32 v133, 0xffff0000, v18
	v_lshlrev_b32_e32 v202, 16, v19
	v_and_b32_e32 v203, 0xffff0000, v19
	v_pk_mul_f32 v[132:133], v[26:27], v[132:133]
	v_pk_mul_f32 v[202:203], v[28:29], v[202:203]
	v_cvt_pk_bf16_f32 v18, v132, v133
	v_cvt_pk_bf16_f32 v19, v202, v203
	v_lshlrev_b32_e32 v132, 16, v20
	v_and_b32_e32 v133, 0xffff0000, v20
	v_lshlrev_b32_e32 v202, 16, v21
	v_and_b32_e32 v203, 0xffff0000, v21
	v_pk_mul_f32 v[132:133], v[22:23], v[132:133]
	v_pk_mul_f32 v[202:203], v[24:25], v[202:203]
	v_cvt_pk_bf16_f32 v20, v132, v133
	v_cvt_pk_bf16_f32 v21, v202, v203
	v_lshlrev_b32_e32 v132, 16, v14
	v_and_b32_e32 v133, 0xffff0000, v14
	v_lshlrev_b32_e32 v202, 16, v15
	v_and_b32_e32 v203, 0xffff0000, v15
	v_pk_mul_f32 v[132:133], v[34:35], v[132:133]
	v_pk_mul_f32 v[202:203], v[36:37], v[202:203]
	v_cvt_pk_bf16_f32 v14, v132, v133
	v_cvt_pk_bf16_f32 v15, v202, v203
	v_lshlrev_b32_e32 v132, 16, v16
	v_and_b32_e32 v133, 0xffff0000, v16
	v_lshlrev_b32_e32 v202, 16, v17
	v_and_b32_e32 v203, 0xffff0000, v17
	v_pk_mul_f32 v[132:133], v[30:31], v[132:133]
	v_pk_mul_f32 v[202:203], v[32:33], v[202:203]
	v_cvt_pk_bf16_f32 v16, v132, v133
	v_cvt_pk_bf16_f32 v17, v202, v203
	v_lshlrev_b32_e32 v132, 16, v10
	v_and_b32_e32 v133, 0xffff0000, v10
	v_lshlrev_b32_e32 v202, 16, v11
	v_and_b32_e32 v203, 0xffff0000, v11
	v_pk_mul_f32 v[132:133], v[42:43], v[132:133]
	v_pk_mul_f32 v[202:203], v[44:45], v[202:203]
	v_cvt_pk_bf16_f32 v10, v132, v133
	v_cvt_pk_bf16_f32 v11, v202, v203
	v_lshlrev_b32_e32 v132, 16, v12
	v_and_b32_e32 v133, 0xffff0000, v12
	v_lshlrev_b32_e32 v202, 16, v13
	v_and_b32_e32 v203, 0xffff0000, v13
	v_pk_mul_f32 v[132:133], v[38:39], v[132:133]
	v_pk_mul_f32 v[202:203], v[40:41], v[202:203]
	v_cvt_pk_bf16_f32 v12, v132, v133
	v_cvt_pk_bf16_f32 v13, v202, v203
	v_lshlrev_b32_e32 v132, 16, v6
	v_and_b32_e32 v133, 0xffff0000, v6
	v_lshlrev_b32_e32 v202, 16, v7
	v_and_b32_e32 v203, 0xffff0000, v7
	v_pk_mul_f32 v[132:133], v[100:101], v[132:133]
	v_pk_mul_f32 v[202:203], v[102:103], v[202:203]
	v_cvt_pk_bf16_f32 v6, v132, v133
	v_cvt_pk_bf16_f32 v7, v202, v203
	v_lshlrev_b32_e32 v132, 16, v8
	v_and_b32_e32 v133, 0xffff0000, v8
	v_lshlrev_b32_e32 v202, 16, v9
	v_and_b32_e32 v203, 0xffff0000, v9
	v_pk_mul_f32 v[132:133], v[46:47], v[132:133]
	v_pk_mul_f32 v[202:203], v[48:49], v[202:203]
	v_cvt_pk_bf16_f32 v8, v132, v133
	v_cvt_pk_bf16_f32 v9, v202, v203
	global_load_dwordx4 v[22:25], v[80:81], off offset:-3072
	global_load_dwordx4 v[26:29], v[80:81], off offset:1024
	global_load_dwordx4 v[30:33], v[84:85], off offset:-3072
	global_load_dwordx4 v[34:37], v[84:85], off offset:1024
	global_load_dwordx4 v[38:41], v[88:89], off offset:-3072
	global_load_dwordx4 v[42:45], v[88:89], off offset:1024
	global_load_dwordx4 v[46:49], v[78:79], off offset:-3072
	global_load_dwordx4 v[100:103], v[78:79], off offset:1024
	s_waitcnt vmcnt(15)
; DI f32x4 mfma32(bf16x8 a, bf16x8 b, f32x4 c) { return __builtin_amdgcn_mfma_f32_16x16x32_bf16(a, b, c, 0, 0, 0); }
; DI void phase_hg3(const Ctx& c, LAS unsigned char* lds, int g, int l, const bf16* PROJ, const bf16* ST, const bf16* RT, const float* GC, const bf16* KT1, const bf16* QTB, bf16* MIX, int bid, int nb, int tid) {
;     ...
;             { const int sq_ = cgk / ncs, cs = cgk - sq_ * ncs, p = dir ? ncs - 1 - cs : cs, blk = p >> 3;
;               if (blk > 0) { const size_t rr = (size_t)((sq_ * 8 + h * 2 + dir) * rps + blk);
; #pragma unroll
;                 for (int ks = 0; ks < 4; ++ks) { const float* gp = GC + su * 128 + ks * 32 + gq * 8; const bf16x8 q2 = scale8(qt[ks], *(const f32x4*)gp, *(const f32x4*)(gp + 4));
; #pragma unroll
;                     for (int vt = 0; vt < 8; ++vt) sa[0][vt] = *(const bf16x8*)(RT + rr * 16384 + ((vt * 4 + ks) * 64 + lane) * 8);
; #pragma unroll
;                     for (int vt = 0; vt < 8; ++vt) o[vt] = mfma32(sa[0][vt], q2, o[vt]); } } }
	v_mfma_f32_16x16x32_bf16 v[66:69], v[104:107], v[18:21], v[66:69]
	s_waitcnt vmcnt(14)
	v_mfma_f32_16x16x32_bf16 v[70:73], v[108:111], v[18:21], v[70:73]
	s_waitcnt vmcnt(13)
	v_mfma_f32_16x16x32_bf16 v[74:77], v[112:115], v[18:21], v[74:77]
	s_waitcnt vmcnt(12)
	v_mfma_f32_16x16x32_bf16 v[62:65], v[116:119], v[18:21], v[62:65]
	s_waitcnt vmcnt(11)
	v_mfma_f32_16x16x32_bf16 v[54:57], v[120:123], v[18:21], v[54:57]
	s_waitcnt vmcnt(10)
	v_mfma_f32_16x16x32_bf16 v[58:61], v[124:127], v[18:21], v[58:61]
	s_waitcnt vmcnt(9)
	v_mfma_f32_16x16x32_bf16 v[94:97], v[128:131], v[18:21], v[94:97]
	s_waitcnt vmcnt(8)
	v_mfma_f32_16x16x32_bf16 v[90:93], v[138:141], v[18:21], v[90:93]
	global_load_dwordx4 v[104:107], v[80:81], off offset:-2048
	global_load_dwordx4 v[108:111], v[80:81], off offset:2048
	global_load_dwordx4 v[112:115], v[84:85], off offset:-2048
	global_load_dwordx4 v[116:119], v[84:85], off offset:2048
	global_load_dwordx4 v[120:123], v[88:89], off offset:-2048
	global_load_dwordx4 v[124:127], v[88:89], off offset:2048
	global_load_dwordx4 v[128:131], v[78:79], off offset:-2048
	global_load_dwordx4 v[138:141], v[78:79], off offset:2048
	s_waitcnt vmcnt(15)
	v_mfma_f32_16x16x32_bf16 v[66:69], v[22:25], v[14:17], v[66:69]
	s_waitcnt vmcnt(14)
	v_mfma_f32_16x16x32_bf16 v[70:73], v[26:29], v[14:17], v[70:73]
	s_waitcnt vmcnt(13)
	v_mfma_f32_16x16x32_bf16 v[74:77], v[30:33], v[14:17], v[74:77]
	s_waitcnt vmcnt(12)
	v_mfma_f32_16x16x32_bf16 v[62:65], v[34:37], v[14:17], v[62:65]
	s_waitcnt vmcnt(11)
	v_mfma_f32_16x16x32_bf16 v[54:57], v[38:41], v[14:17], v[54:57]
	s_waitcnt vmcnt(10)
	v_mfma_f32_16x16x32_bf16 v[58:61], v[42:45], v[14:17], v[58:61]
	s_waitcnt vmcnt(9)
	v_mfma_f32_16x16x32_bf16 v[94:97], v[46:49], v[14:17], v[94:97]
	s_waitcnt vmcnt(8)
	v_mfma_f32_16x16x32_bf16 v[90:93], v[100:103], v[14:17], v[90:93]
	global_load_dwordx4 v[22:25], v[80:81], off offset:-1024
	global_load_dwordx4 v[26:29], v[80:81], off offset:3072
	global_load_dwordx4 v[30:33], v[84:85], off offset:-1024
	global_load_dwordx4 v[34:37], v[84:85], off offset:3072
	global_load_dwordx4 v[38:41], v[88:89], off offset:-1024
	global_load_dwordx4 v[42:45], v[88:89], off offset:3072
	global_load_dwordx4 v[46:49], v[78:79], off offset:-1024
	global_load_dwordx4 v[100:103], v[78:79], off offset:3072
	s_waitcnt vmcnt(15)
	v_mfma_f32_16x16x32_bf16 v[66:69], v[104:107], v[10:13], v[66:69]
	s_waitcnt vmcnt(14)
	v_mfma_f32_16x16x32_bf16 v[70:73], v[108:111], v[10:13], v[70:73]
	s_waitcnt vmcnt(13)
	v_mfma_f32_16x16x32_bf16 v[74:77], v[112:115], v[10:13], v[74:77]
	s_waitcnt vmcnt(12)
	v_mfma_f32_16x16x32_bf16 v[62:65], v[116:119], v[10:13], v[62:65]
	s_waitcnt vmcnt(11)
	v_mfma_f32_16x16x32_bf16 v[54:57], v[120:123], v[10:13], v[54:57]
	s_waitcnt vmcnt(10)
	v_mfma_f32_16x16x32_bf16 v[58:61], v[124:127], v[10:13], v[58:61]
	s_waitcnt vmcnt(9)
	v_mfma_f32_16x16x32_bf16 v[94:97], v[128:131], v[10:13], v[94:97]
	s_waitcnt vmcnt(8)
	v_mfma_f32_16x16x32_bf16 v[90:93], v[138:141], v[10:13], v[90:93]
	s_waitcnt vmcnt(7)
	v_mfma_f32_16x16x32_bf16 v[66:69], v[22:25], v[6:9], v[66:69]
	s_waitcnt vmcnt(6)
	v_mfma_f32_16x16x32_bf16 v[70:73], v[26:29], v[6:9], v[70:73]
	s_waitcnt vmcnt(5)
	v_mfma_f32_16x16x32_bf16 v[74:77], v[30:33], v[6:9], v[74:77]
	s_waitcnt vmcnt(4)
	v_mfma_f32_16x16x32_bf16 v[62:65], v[34:37], v[6:9], v[62:65]
	s_waitcnt vmcnt(3)
	v_mfma_f32_16x16x32_bf16 v[54:57], v[38:41], v[6:9], v[54:57]
	s_waitcnt vmcnt(2)
	v_mfma_f32_16x16x32_bf16 v[58:61], v[42:45], v[6:9], v[58:61]
	s_waitcnt vmcnt(1)
	v_mfma_f32_16x16x32_bf16 v[94:97], v[46:49], v[6:9], v[94:97]
	s_waitcnt vmcnt(0)
	v_mfma_f32_16x16x32_bf16 v[90:93], v[100:103], v[6:9], v[90:93]
	s_branch .LBB0_405

; DI f32x4 mfma32(bf16x8 a, bf16x8 b, f32x4 c) { return __builtin_amdgcn_mfma_f32_16x16x32_bf16(a, b, c, 0, 0, 0); }
; DI void phase_hg3(const Ctx& c, LAS unsigned char* lds, int g, int l, const bf16* PROJ, const bf16* ST, const bf16* RT, const float* GC, const bf16* KT1, const bf16* QTB, bf16* MIX, int bid, int nb, int tid) {
;     ...
; #pragma unroll
;             for (int ks = 0; ks < 4; ++ks) {
;                 if (ks < 3) {
; #pragma unroll
;                     for (int vt = 0; vt < 8; ++vt) sa[(ks + 1) & 1][vt] = *(const bf16x8*)(ST + su * 16384 + ((vt * 4 + ks + 1) * 64 + lane) * 8); }
; #pragma unroll
;                 for (int vt = 0; vt < 8; ++vt) o[vt] = mfma32(sa[ks & 1][vt], qt[ks], o[vt]);
;             }
.LBB0_409:
	s_or_b64 exec, exec, vcc
	s_mov_b64 vcc, 0x1000
	v_lshl_add_u64 v[134:135], vcc, 0, v[184:185]
	s_mov_b64 vcc, 0x3000
	v_lshl_add_u64 v[136:137], vcc, 0, v[184:185]
	s_mov_b64 vcc, 0x5000
	v_lshl_add_u64 v[138:139], vcc, 0, v[184:185]
	s_mov_b64 vcc, 0x7000
	v_lshl_add_u64 v[140:141], vcc, 0, v[184:185]
	global_load_dwordx4 v[86:89], v[134:135], off offset:-3072
	global_load_dwordx4 v[90:93], v[134:135], off offset:1024
	global_load_dwordx4 v[94:97], v[136:137], off offset:-3072
	global_load_dwordx4 v[98:101], v[136:137], off offset:1024
	global_load_dwordx4 v[102:105], v[138:139], off offset:-3072
	global_load_dwordx4 v[106:109], v[138:139], off offset:1024
	global_load_dwordx4 v[110:113], v[140:141], off offset:-3072
	global_load_dwordx4 v[114:117], v[140:141], off offset:1024
	global_load_dwordx4 v[118:121], v[134:135], off offset:-2048
	global_load_dwordx4 v[122:125], v[134:135], off offset:2048
	global_load_dwordx4 v[126:129], v[136:137], off offset:-2048
	global_load_dwordx4 v[130:133], v[136:137], off offset:2048
	s_waitcnt vmcnt(12)
	v_mfma_f32_16x16x32_bf16 v[50:53], v[50:53], v[42:45], v[82:85]
	s_movk_i32 s1, 0x4000
	v_mfma_f32_16x16x32_bf16 v[46:49], v[46:49], v[42:45], v[78:81]
	s_movk_i32 s19, 0x6000
	v_mfma_f32_16x16x32_bf16 v[38:41], v[38:41], v[42:45], v[70:73]
	s_not_b32 s0, s33
	v_mfma_f32_16x16x32_bf16 v[34:37], v[34:37], v[42:45], v[66:69]
	v_readlane_b32 s33, v254, 53
	v_mfma_f32_16x16x32_bf16 v[30:33], v[30:33], v[42:45], v[74:77]
	s_add_i32 s0, s33, s0
	v_mfma_f32_16x16x32_bf16 v[26:29], v[26:29], v[42:45], v[62:65]
	s_ashr_i32 s0, s0, 3
	v_mfma_f32_16x16x32_bf16 v[22:25], v[22:25], v[42:45], v[58:61]
	s_cmp_lt_i32 s0, 1
	v_mfma_f32_16x16x32_bf16 v[18:21], v[18:21], v[42:45], v[54:57]
	global_load_dwordx4 v[82:85], v[138:139], off offset:-2048
	global_load_dwordx4 v[78:81], v[138:139], off offset:2048
	global_load_dwordx4 v[70:73], v[140:141], off offset:-2048
	global_load_dwordx4 v[66:69], v[140:141], off offset:2048
	global_load_dwordx4 v[74:77], v[134:135], off offset:-1024
	global_load_dwordx4 v[62:65], v[134:135], off offset:3072
	global_load_dwordx4 v[58:61], v[136:137], off offset:-1024
	global_load_dwordx4 v[54:57], v[136:137], off offset:3072
	s_waitcnt vmcnt(19)
	v_mfma_f32_16x16x32_bf16 v[50:53], v[86:89], v[14:17], v[50:53]
	s_waitcnt vmcnt(18)
	v_mfma_f32_16x16x32_bf16 v[46:49], v[90:93], v[14:17], v[46:49]
	s_waitcnt vmcnt(17)
	v_mfma_f32_16x16x32_bf16 v[38:41], v[94:97], v[14:17], v[38:41]
	s_waitcnt vmcnt(16)
	v_mfma_f32_16x16x32_bf16 v[34:37], v[98:101], v[14:17], v[34:37]
	s_waitcnt vmcnt(15)
	v_mfma_f32_16x16x32_bf16 v[30:33], v[102:105], v[14:17], v[30:33]
	s_waitcnt vmcnt(14)
	v_mfma_f32_16x16x32_bf16 v[26:29], v[106:109], v[14:17], v[26:29]
	s_waitcnt vmcnt(13)
	v_mfma_f32_16x16x32_bf16 v[22:25], v[110:113], v[14:17], v[22:25]
	s_waitcnt vmcnt(12)
	v_mfma_f32_16x16x32_bf16 v[18:21], v[114:117], v[14:17], v[18:21]
	global_load_dwordx4 v[86:89], v[138:139], off offset:-1024
	global_load_dwordx4 v[90:93], v[138:139], off offset:3072
	global_load_dwordx4 v[94:97], v[140:141], off offset:-1024
	global_load_dwordx4 v[98:101], v[140:141], off offset:3072
	s_waitcnt vmcnt(15)
	v_mfma_f32_16x16x32_bf16 v[50:53], v[118:121], v[10:13], v[50:53]
	s_waitcnt vmcnt(14)
	v_mfma_f32_16x16x32_bf16 v[46:49], v[122:125], v[10:13], v[46:49]
	s_waitcnt vmcnt(13)
	v_mfma_f32_16x16x32_bf16 v[38:41], v[126:129], v[10:13], v[38:41]
	s_waitcnt vmcnt(12)
	v_mfma_f32_16x16x32_bf16 v[34:37], v[130:133], v[10:13], v[34:37]
	s_waitcnt vmcnt(11)
	v_mfma_f32_16x16x32_bf16 v[30:33], v[82:85], v[10:13], v[30:33]
	s_waitcnt vmcnt(10)
	v_mfma_f32_16x16x32_bf16 v[26:29], v[78:81], v[10:13], v[26:29]
	s_waitcnt vmcnt(9)
	v_mfma_f32_16x16x32_bf16 v[22:25], v[70:73], v[10:13], v[22:25]
	s_waitcnt vmcnt(8)
	v_mfma_f32_16x16x32_bf16 v[18:21], v[66:69], v[10:13], v[18:21]
	s_waitcnt vmcnt(7)
	v_mfma_f32_16x16x32_bf16 v[50:53], v[74:77], v[6:9], v[50:53]
	s_waitcnt vmcnt(6)
	v_mfma_f32_16x16x32_bf16 v[46:49], v[62:65], v[6:9], v[46:49]
	s_waitcnt vmcnt(5)
	v_mfma_f32_16x16x32_bf16 v[38:41], v[58:61], v[6:9], v[38:41]
	s_waitcnt vmcnt(4)
	v_mfma_f32_16x16x32_bf16 v[34:37], v[54:57], v[6:9], v[34:37]
	s_waitcnt vmcnt(3)
	v_mfma_f32_16x16x32_bf16 v[30:33], v[86:89], v[6:9], v[30:33]
	s_waitcnt vmcnt(2)
	v_mfma_f32_16x16x32_bf16 v[26:29], v[90:93], v[6:9], v[26:29]
	s_waitcnt vmcnt(1)
	v_mfma_f32_16x16x32_bf16 v[22:25], v[94:97], v[6:9], v[22:25]
	s_waitcnt vmcnt(0)
	v_mfma_f32_16x16x32_bf16 v[18:21], v[98:101], v[6:9], v[18:21]
	s_cbranch_scc1 .LBB0_395
; DI f32x4 mfma32(bf16x8 a, bf16x8 b, f32x4 c) { return __builtin_amdgcn_mfma_f32_16x16x32_bf16(a, b, c, 0, 0, 0); }
; DI void phase_hg3(const Ctx& c, LAS unsigned char* lds, int g, int l, const bf16* PROJ, const bf16* ST, const bf16* RT, const float* GC, const bf16* KT1, const bf16* QTB, bf16* MIX, int bid, int nb, int tid) {
;     ...
;             { const int sq_ = cgk / ncs, cs = cgk - sq_ * ncs, p = dir ? ncs - 1 - cs : cs, blk = p >> 3;
;               if (blk > 0) { const size_t rr = (size_t)((sq_ * 8 + h * 2 + dir) * rps + blk);
; #pragma unroll
;                 for (int ks = 0; ks < 4; ++ks) { const float* gp = GC + su * 128 + ks * 32 + gq * 8; const bf16x8 q2 = scale8(qt[ks], *(const f32x4*)gp, *(const f32x4*)(gp + 4));
; #pragma unroll
;                     for (int vt = 0; vt < 8; ++vt) sa[0][vt] = *(const bf16x8*)(RT + rr * 16384 + ((vt * 4 + ks) * 64 + lane) * 8);
; #pragma unroll
;                     for (int vt = 0; vt < 8; ++vt) o[vt] = mfma32(sa[0][vt], q2, o[vt]); } } }
	v_or_b32_e32 v54, 1, v181
	v_readlane_b32 s33, v254, 44
	s_nop 1
	v_lshlrev_b32_e32 v54, s33, v54
	v_add_u32_e32 v56, s0, v54
	v_lshlrev_b64 v[54:55], 9, v[182:183]
	v_ashrrev_i32_e32 v57, 31, v56
	v_lshl_add_u64 v[54:55], v[2:3], 0, v[54:55]
	v_lshlrev_b64 v[68:69], 15, v[56:57]
	v_lshl_add_u64 v[56:57], v[146:147], 0, v[68:69]
	s_movk_i32 s0, 0x3000
	s_mov_b64 vcc, 0x1000
	v_lshl_add_u64 v[58:59], vcc, 0, v[56:57]
	s_mov_b64 vcc, 0x3000
	v_lshl_add_u64 v[60:61], vcc, 0, v[56:57]
	s_mov_b64 vcc, 0x5000
	v_lshl_add_u64 v[62:63], vcc, 0, v[56:57]
	s_mov_b64 vcc, 0x7000
	v_lshl_add_u64 v[72:73], vcc, 0, v[56:57]
	global_load_dwordx4 v[64:67], v[54:55], off offset:16
	global_load_dwordx4 v[68:71], v[54:55], off
	global_load_dwordx4 v[74:77], v[54:55], off offset:144
	global_load_dwordx4 v[78:81], v[54:55], off offset:128
	global_load_dwordx4 v[82:85], v[54:55], off offset:272
	global_load_dwordx4 v[86:89], v[54:55], off offset:256
	global_load_dwordx4 v[90:93], v[54:55], off offset:400
	global_load_dwordx4 v[94:97], v[54:55], off offset:384
	global_load_dwordx4 v[98:101], v[58:59], off offset:-4096
	global_load_dwordx4 v[102:105], v[58:59], off
	global_load_dwordx4 v[106:109], v[60:61], off offset:-4096
	global_load_dwordx4 v[110:113], v[60:61], off
	global_load_dwordx4 v[114:117], v[62:63], off offset:-4096
	global_load_dwordx4 v[118:121], v[62:63], off
	global_load_dwordx4 v[122:125], v[72:73], off offset:-4096
	global_load_dwordx4 v[126:129], v[72:73], off
	s_waitcnt vmcnt(8)
	v_lshlrev_b32_e32 v130, 16, v42
	v_and_b32_e32 v131, 0xffff0000, v42
	v_lshlrev_b32_e32 v132, 16, v43
	v_and_b32_e32 v133, 0xffff0000, v43
	v_pk_mul_f32 v[130:131], v[68:69], v[130:131]
	v_pk_mul_f32 v[132:133], v[70:71], v[132:133]
	v_cvt_pk_bf16_f32 v42, v130, v131
	v_cvt_pk_bf16_f32 v43, v132, v133
	v_lshlrev_b32_e32 v130, 16, v44
	v_and_b32_e32 v131, 0xffff0000, v44
	v_lshlrev_b32_e32 v132, 16, v45
	v_and_b32_e32 v133, 0xffff0000, v45
	v_pk_mul_f32 v[130:131], v[64:65], v[130:131]
	v_pk_mul_f32 v[132:133], v[66:67], v[132:133]
	v_cvt_pk_bf16_f32 v44, v130, v131
	v_cvt_pk_bf16_f32 v45, v132, v133
	v_lshlrev_b32_e32 v130, 16, v14
	v_and_b32_e32 v131, 0xffff0000, v14
	v_lshlrev_b32_e32 v132, 16, v15
	v_and_b32_e32 v133, 0xffff0000, v15
	v_pk_mul_f32 v[130:131], v[78:79], v[130:131]
	v_pk_mul_f32 v[132:133], v[80:81], v[132:133]
	v_cvt_pk_bf16_f32 v14, v130, v131
	v_cvt_pk_bf16_f32 v15, v132, v133
	v_lshlrev_b32_e32 v130, 16, v16
	v_and_b32_e32 v131, 0xffff0000, v16
	v_lshlrev_b32_e32 v132, 16, v17
	v_and_b32_e32 v133, 0xffff0000, v17
	v_pk_mul_f32 v[130:131], v[74:75], v[130:131]
	v_pk_mul_f32 v[132:133], v[76:77], v[132:133]
	v_cvt_pk_bf16_f32 v16, v130, v131
	v_cvt_pk_bf16_f32 v17, v132, v133
	v_lshlrev_b32_e32 v130, 16, v10
	v_and_b32_e32 v131, 0xffff0000, v10
	v_lshlrev_b32_e32 v132, 16, v11
	v_and_b32_e32 v133, 0xffff0000, v11
	v_pk_mul_f32 v[130:131], v[86:87], v[130:131]
	v_pk_mul_f32 v[132:133], v[88:89], v[132:133]
	v_cvt_pk_bf16_f32 v10, v130, v131
	v_cvt_pk_bf16_f32 v11, v132, v133
	v_lshlrev_b32_e32 v130, 16, v12
	v_and_b32_e32 v131, 0xffff0000, v12
	v_lshlrev_b32_e32 v132, 16, v13
	v_and_b32_e32 v133, 0xffff0000, v13
	v_pk_mul_f32 v[130:131], v[82:83], v[130:131]
	v_pk_mul_f32 v[132:133], v[84:85], v[132:133]
	v_cvt_pk_bf16_f32 v12, v130, v131
	v_cvt_pk_bf16_f32 v13, v132, v133
	v_lshlrev_b32_e32 v130, 16, v6
	v_and_b32_e32 v131, 0xffff0000, v6
	v_lshlrev_b32_e32 v132, 16, v7
	v_and_b32_e32 v133, 0xffff0000, v7
	v_pk_mul_f32 v[130:131], v[94:95], v[130:131]
	v_pk_mul_f32 v[132:133], v[96:97], v[132:133]
	v_cvt_pk_bf16_f32 v6, v130, v131
	v_cvt_pk_bf16_f32 v7, v132, v133
	v_lshlrev_b32_e32 v130, 16, v8
	v_and_b32_e32 v131, 0xffff0000, v8
	v_lshlrev_b32_e32 v132, 16, v9
	v_and_b32_e32 v133, 0xffff0000, v9
	v_pk_mul_f32 v[130:131], v[90:91], v[130:131]
	v_pk_mul_f32 v[132:133], v[92:93], v[132:133]
	v_cvt_pk_bf16_f32 v8, v130, v131
	v_cvt_pk_bf16_f32 v9, v132, v133
	global_load_dwordx4 v[64:67], v[58:59], off offset:-3072
	global_load_dwordx4 v[68:71], v[58:59], off offset:1024
	global_load_dwordx4 v[74:77], v[60:61], off offset:-3072
	global_load_dwordx4 v[78:81], v[60:61], off offset:1024
	global_load_dwordx4 v[82:85], v[62:63], off offset:-3072
	global_load_dwordx4 v[86:89], v[62:63], off offset:1024
	global_load_dwordx4 v[90:93], v[72:73], off offset:-3072
	global_load_dwordx4 v[94:97], v[72:73], off offset:1024
	s_waitcnt vmcnt(15)
; DI f32x4 mfma32(bf16x8 a, bf16x8 b, f32x4 c) { return __builtin_amdgcn_mfma_f32_16x16x32_bf16(a, b, c, 0, 0, 0); }
; DI void phase_hg3(const Ctx& c, LAS unsigned char* lds, int g, int l, const bf16* PROJ, const bf16* ST, const bf16* RT, const float* GC, const bf16* KT1, const bf16* QTB, bf16* MIX, int bid, int nb, int tid) {
;     ...
;             { const int sq_ = cgk / ncs, cs = cgk - sq_ * ncs, p = dir ? ncs - 1 - cs : cs, blk = p >> 3;
;               if (blk > 0) { const size_t rr = (size_t)((sq_ * 8 + h * 2 + dir) * rps + blk);
; #pragma unroll
;                 for (int ks = 0; ks < 4; ++ks) { const float* gp = GC + su * 128 + ks * 32 + gq * 8; const bf16x8 q2 = scale8(qt[ks], *(const f32x4*)gp, *(const f32x4*)(gp + 4));
; #pragma unroll
;                     for (int vt = 0; vt < 8; ++vt) sa[0][vt] = *(const bf16x8*)(RT + rr * 16384 + ((vt * 4 + ks) * 64 + lane) * 8);
; #pragma unroll
;                     for (int vt = 0; vt < 8; ++vt) o[vt] = mfma32(sa[0][vt], q2, o[vt]); } } }
	v_mfma_f32_16x16x32_bf16 v[50:53], v[98:101], v[42:45], v[50:53]
	s_waitcnt vmcnt(14)
	v_mfma_f32_16x16x32_bf16 v[46:49], v[102:105], v[42:45], v[46:49]
	s_waitcnt vmcnt(13)
	v_mfma_f32_16x16x32_bf16 v[38:41], v[106:109], v[42:45], v[38:41]
	s_waitcnt vmcnt(12)
	v_mfma_f32_16x16x32_bf16 v[34:37], v[110:113], v[42:45], v[34:37]
	s_waitcnt vmcnt(11)
	v_mfma_f32_16x16x32_bf16 v[30:33], v[114:117], v[42:45], v[30:33]
	s_waitcnt vmcnt(10)
	v_mfma_f32_16x16x32_bf16 v[26:29], v[118:121], v[42:45], v[26:29]
	s_waitcnt vmcnt(9)
	v_mfma_f32_16x16x32_bf16 v[22:25], v[122:125], v[42:45], v[22:25]
	s_waitcnt vmcnt(8)
	v_mfma_f32_16x16x32_bf16 v[18:21], v[126:129], v[42:45], v[18:21]
	global_load_dwordx4 v[98:101], v[58:59], off offset:-2048
	global_load_dwordx4 v[102:105], v[58:59], off offset:2048
	global_load_dwordx4 v[106:109], v[60:61], off offset:-2048
	global_load_dwordx4 v[110:113], v[60:61], off offset:2048
	global_load_dwordx4 v[114:117], v[62:63], off offset:-2048
	global_load_dwordx4 v[118:121], v[62:63], off offset:2048
	global_load_dwordx4 v[122:125], v[72:73], off offset:-2048
	global_load_dwordx4 v[126:129], v[72:73], off offset:2048
	s_waitcnt vmcnt(15)
	v_mfma_f32_16x16x32_bf16 v[50:53], v[64:67], v[14:17], v[50:53]
	s_waitcnt vmcnt(14)
	v_mfma_f32_16x16x32_bf16 v[46:49], v[68:71], v[14:17], v[46:49]
	s_waitcnt vmcnt(13)
	v_mfma_f32_16x16x32_bf16 v[38:41], v[74:77], v[14:17], v[38:41]
	s_waitcnt vmcnt(12)
	v_mfma_f32_16x16x32_bf16 v[34:37], v[78:81], v[14:17], v[34:37]
	s_waitcnt vmcnt(11)
	v_mfma_f32_16x16x32_bf16 v[30:33], v[82:85], v[14:17], v[30:33]
	s_waitcnt vmcnt(10)
	v_mfma_f32_16x16x32_bf16 v[26:29], v[86:89], v[14:17], v[26:29]
	s_waitcnt vmcnt(9)
	v_mfma_f32_16x16x32_bf16 v[22:25], v[90:93], v[14:17], v[22:25]
	s_waitcnt vmcnt(8)
	v_mfma_f32_16x16x32_bf16 v[18:21], v[94:97], v[14:17], v[18:21]
	global_load_dwordx4 v[64:67], v[58:59], off offset:-1024
	global_load_dwordx4 v[68:71], v[58:59], off offset:3072
	global_load_dwordx4 v[74:77], v[60:61], off offset:-1024
	global_load_dwordx4 v[78:81], v[60:61], off offset:3072
	global_load_dwordx4 v[82:85], v[62:63], off offset:-1024
	global_load_dwordx4 v[86:89], v[62:63], off offset:3072
	global_load_dwordx4 v[90:93], v[72:73], off offset:-1024
	global_load_dwordx4 v[94:97], v[72:73], off offset:3072
	s_waitcnt vmcnt(15)
	v_mfma_f32_16x16x32_bf16 v[50:53], v[98:101], v[10:13], v[50:53]
	s_waitcnt vmcnt(14)
	v_mfma_f32_16x16x32_bf16 v[46:49], v[102:105], v[10:13], v[46:49]
	s_waitcnt vmcnt(13)
	v_mfma_f32_16x16x32_bf16 v[38:41], v[106:109], v[10:13], v[38:41]
	s_waitcnt vmcnt(12)
	v_mfma_f32_16x16x32_bf16 v[34:37], v[110:113], v[10:13], v[34:37]
	s_waitcnt vmcnt(11)
	v_mfma_f32_16x16x32_bf16 v[30:33], v[114:117], v[10:13], v[30:33]
	s_waitcnt vmcnt(10)
	v_mfma_f32_16x16x32_bf16 v[26:29], v[118:121], v[10:13], v[26:29]
	s_waitcnt vmcnt(9)
	v_mfma_f32_16x16x32_bf16 v[22:25], v[122:125], v[10:13], v[22:25]
	s_waitcnt vmcnt(8)
	v_mfma_f32_16x16x32_bf16 v[18:21], v[126:129], v[10:13], v[18:21]
	s_waitcnt vmcnt(7)
	v_mfma_f32_16x16x32_bf16 v[50:53], v[64:67], v[6:9], v[50:53]
	s_waitcnt vmcnt(6)
	v_mfma_f32_16x16x32_bf16 v[46:49], v[68:71], v[6:9], v[46:49]
	s_waitcnt vmcnt(5)
	v_mfma_f32_16x16x32_bf16 v[38:41], v[74:77], v[6:9], v[38:41]
	s_waitcnt vmcnt(4)
	v_mfma_f32_16x16x32_bf16 v[34:37], v[78:81], v[6:9], v[34:37]
	s_waitcnt vmcnt(3)
	v_mfma_f32_16x16x32_bf16 v[30:33], v[82:85], v[6:9], v[30:33]
	s_waitcnt vmcnt(2)
	v_mfma_f32_16x16x32_bf16 v[26:29], v[86:89], v[6:9], v[26:29]
	s_waitcnt vmcnt(1)
	v_mfma_f32_16x16x32_bf16 v[22:25], v[90:93], v[6:9], v[22:25]
	s_waitcnt vmcnt(0)
	v_mfma_f32_16x16x32_bf16 v[18:21], v[94:97], v[6:9], v[18:21]
	s_branch .LBB0_395
